# S5 prompt scan (A2): T*U MFMA loops of both passes unrolled with ring-buffered table/activation loads instead of load-wait-MFMA per step
# speedup vs baseline: 1.0058x; 1.0058x over previous
.LBB0_786:
	s_waitcnt vmcnt(0) lgkmcnt(0)
	v_readfirstlane_b32 s46, v198
	v_readfirstlane_b32 s47, v199
	s_nop 0
	v_subrev_u32_e32 v142, s46, v198
	s_add_u32 s46, s46, 0x1000
	s_addc_u32 s47, s47, 0
	s_add_u32 s48, s46, 0x2000
	s_addc_u32 s49, s47, 0
	s_mov_b32 s50, 0x2800
	s_mov_b32 s51, 0
	s_nop 4
	global_load_dwordx4 v[132:135], v[136:137], off
	v_lshl_add_u64 v[136:137], v[136:137], 0, s[50:51]
	global_load_dwordx4 v[234:237], v[136:137], off
	v_lshl_add_u64 v[136:137], v[136:137], 0, s[50:51]
	global_load_dwordx4 v[238:241], v[136:137], off
	v_lshl_add_u64 v[136:137], v[136:137], 0, s[50:51]
	global_load_dwordx4 v[138:141], v142, s[46:47] offset:-3072
	global_load_dwordx4 v[242:245], v142, s[46:47] offset:-1024
	global_load_dwordx4 v[246:249], v142, s[46:47] offset:1024
	global_load_dwordx4 v[250:253], v142, s[46:47] offset:3072
	s_waitcnt vmcnt(3)
	v_mfma_f32_32x32x16_bf16 v[116:131], v[138:141], v[132:135], v[116:131]
	global_load_dwordx4 v[138:141], v142, s[48:49] offset:-3072
	s_waitcnt vmcnt(3)
	v_mfma_f32_32x32x16_bf16 v[100:115], v[242:245], v[132:135], v[100:115]
	global_load_dwordx4 v[242:245], v142, s[48:49] offset:-1024
	s_waitcnt vmcnt(3)
	v_mfma_f32_32x32x16_bf16 v[84:99], v[246:249], v[132:135], v[84:99]
	global_load_dwordx4 v[246:249], v142, s[48:49] offset:1024
	s_waitcnt vmcnt(3)
	v_mfma_f32_32x32x16_bf16 v[68:83], v[250:253], v[132:135], v[68:83]
	global_load_dwordx4 v[250:253], v142, s[48:49] offset:3072
	s_waitcnt vmcnt(3)
	v_mfma_f32_32x32x16_bf16 v[52:67], v[138:141], v[132:135], v[52:67]
	global_load_dwordx4 v[138:141], v142, s[46:47] offset:-4096
	s_waitcnt vmcnt(3)
	v_mfma_f32_32x32x16_bf16 v[36:51], v[242:245], v[132:135], v[36:51]
	global_load_dwordx4 v[242:245], v142, s[46:47] offset:-2048
	s_waitcnt vmcnt(3)
	v_mfma_f32_32x32x16_bf16 v[20:35], v[246:249], v[132:135], v[20:35]
	global_load_dwordx4 v[246:249], v142, s[46:47]
	s_waitcnt vmcnt(3)
	v_mfma_f32_32x32x16_bf16 v[4:19], v[250:253], v[132:135], v[4:19]
	global_load_dwordx4 v[132:135], v[136:137], off
	v_lshl_add_u64 v[136:137], v[136:137], 0, s[50:51]
	global_load_dwordx4 v[250:253], v142, s[46:47] offset:2048
	s_waitcnt vmcnt(4)
	v_mfma_f32_32x32x16_bf16 v[116:131], v[138:141], v[234:237], v[116:131]
	global_load_dwordx4 v[138:141], v142, s[48:49] offset:-4096
	s_waitcnt vmcnt(4)
	v_mfma_f32_32x32x16_bf16 v[100:115], v[242:245], v[234:237], v[100:115]
	global_load_dwordx4 v[242:245], v142, s[48:49] offset:-2048
	s_waitcnt vmcnt(4)
	v_mfma_f32_32x32x16_bf16 v[84:99], v[246:249], v[234:237], v[84:99]
	global_load_dwordx4 v[246:249], v142, s[48:49]
	s_waitcnt vmcnt(3)
	v_mfma_f32_32x32x16_bf16 v[68:83], v[250:253], v[234:237], v[68:83]
	global_load_dwordx4 v[250:253], v142, s[48:49] offset:2048
	s_waitcnt vmcnt(3)
	v_mfma_f32_32x32x16_bf16 v[52:67], v[138:141], v[234:237], v[52:67]
	global_load_dwordx4 v[138:141], v142, s[46:47] offset:-3072
	s_waitcnt vmcnt(3)
	v_mfma_f32_32x32x16_bf16 v[36:51], v[242:245], v[234:237], v[36:51]
	global_load_dwordx4 v[242:245], v142, s[46:47] offset:-1024
	s_waitcnt vmcnt(3)
	v_mfma_f32_32x32x16_bf16 v[20:35], v[246:249], v[234:237], v[20:35]
	global_load_dwordx4 v[246:249], v142, s[46:47] offset:1024
	s_waitcnt vmcnt(3)
	v_mfma_f32_32x32x16_bf16 v[4:19], v[250:253], v[234:237], v[4:19]
	global_load_dwordx4 v[234:237], v[136:137], off
	v_lshl_add_u64 v[136:137], v[136:137], 0, s[50:51]
	global_load_dwordx4 v[250:253], v142, s[46:47] offset:3072
	s_waitcnt vmcnt(4)
	v_mfma_f32_32x32x16_bf16 v[100:115], v[138:141], v[238:241], v[100:115]
	global_load_dwordx4 v[138:141], v142, s[48:49] offset:-3072
	s_waitcnt vmcnt(4)
	v_mfma_f32_32x32x16_bf16 v[84:99], v[242:245], v[238:241], v[84:99]
	global_load_dwordx4 v[242:245], v142, s[48:49] offset:-1024
	s_waitcnt vmcnt(4)
	v_mfma_f32_32x32x16_bf16 v[68:83], v[246:249], v[238:241], v[68:83]
	global_load_dwordx4 v[246:249], v142, s[48:49] offset:1024
	s_waitcnt vmcnt(3)
	v_mfma_f32_32x32x16_bf16 v[52:67], v[250:253], v[238:241], v[52:67]
	global_load_dwordx4 v[250:253], v142, s[46:47] offset:-4096
	s_waitcnt vmcnt(3)
	v_mfma_f32_32x32x16_bf16 v[36:51], v[138:141], v[238:241], v[36:51]
	global_load_dwordx4 v[138:141], v142, s[46:47] offset:-2048
	s_waitcnt vmcnt(3)
	v_mfma_f32_32x32x16_bf16 v[20:35], v[242:245], v[238:241], v[20:35]
	global_load_dwordx4 v[242:245], v142, s[46:47]
	s_waitcnt vmcnt(3)
	v_mfma_f32_32x32x16_bf16 v[4:19], v[246:249], v[238:241], v[4:19]
	global_load_dwordx4 v[238:241], v[136:137], off
	v_lshl_add_u64 v[136:137], v[136:137], 0, s[50:51]
	global_load_dwordx4 v[246:249], v142, s[46:47] offset:2048
	s_waitcnt vmcnt(4)
	v_mfma_f32_32x32x16_bf16 v[100:115], v[250:253], v[132:135], v[100:115]
	global_load_dwordx4 v[250:253], v142, s[48:49] offset:-4096
	s_waitcnt vmcnt(4)
	v_mfma_f32_32x32x16_bf16 v[84:99], v[138:141], v[132:135], v[84:99]
	global_load_dwordx4 v[138:141], v142, s[48:49] offset:-2048
	s_waitcnt vmcnt(4)
	v_mfma_f32_32x32x16_bf16 v[68:83], v[242:245], v[132:135], v[68:83]
	global_load_dwordx4 v[242:245], v142, s[48:49]
	s_waitcnt vmcnt(3)
	v_mfma_f32_32x32x16_bf16 v[52:67], v[246:249], v[132:135], v[52:67]
	global_load_dwordx4 v[246:249], v142, s[46:47] offset:-3072
	s_waitcnt vmcnt(3)
	v_mfma_f32_32x32x16_bf16 v[36:51], v[250:253], v[132:135], v[36:51]
	global_load_dwordx4 v[250:253], v142, s[46:47] offset:-1024
	s_waitcnt vmcnt(3)
	v_mfma_f32_32x32x16_bf16 v[20:35], v[138:141], v[132:135], v[20:35]
	global_load_dwordx4 v[138:141], v142, s[46:47] offset:1024
	s_waitcnt vmcnt(3)
	v_mfma_f32_32x32x16_bf16 v[4:19], v[242:245], v[132:135], v[4:19]
	global_load_dwordx4 v[132:135], v[136:137], off
	v_lshl_add_u64 v[136:137], v[136:137], 0, s[50:51]
	global_load_dwordx4 v[242:245], v142, s[46:47] offset:3072
	s_waitcnt vmcnt(4)
	v_mfma_f32_32x32x16_bf16 v[84:99], v[246:249], v[234:237], v[84:99]
	global_load_dwordx4 v[246:249], v142, s[48:49] offset:-3072
	s_waitcnt vmcnt(4)
	v_mfma_f32_32x32x16_bf16 v[68:83], v[250:253], v[234:237], v[68:83]
	global_load_dwordx4 v[250:253], v142, s[48:49] offset:-1024
	s_waitcnt vmcnt(4)
	v_mfma_f32_32x32x16_bf16 v[52:67], v[138:141], v[234:237], v[52:67]
	global_load_dwordx4 v[138:141], v142, s[46:47] offset:-4096
	s_waitcnt vmcnt(3)
	v_mfma_f32_32x32x16_bf16 v[36:51], v[242:245], v[234:237], v[36:51]
	global_load_dwordx4 v[242:245], v142, s[46:47] offset:-2048
	s_waitcnt vmcnt(3)
	v_mfma_f32_32x32x16_bf16 v[20:35], v[246:249], v[234:237], v[20:35]
	global_load_dwordx4 v[246:249], v142, s[46:47]
	s_waitcnt vmcnt(3)
	v_mfma_f32_32x32x16_bf16 v[4:19], v[250:253], v[234:237], v[4:19]
	global_load_dwordx4 v[234:237], v[136:137], off
	v_lshl_add_u64 v[136:137], v[136:137], 0, s[50:51]
	global_load_dwordx4 v[250:253], v142, s[46:47] offset:2048
	s_waitcnt vmcnt(4)
	v_mfma_f32_32x32x16_bf16 v[84:99], v[138:141], v[238:241], v[84:99]
	global_load_dwordx4 v[138:141], v142, s[48:49] offset:-4096
	s_waitcnt vmcnt(4)
	v_mfma_f32_32x32x16_bf16 v[68:83], v[242:245], v[238:241], v[68:83]
	global_load_dwordx4 v[242:245], v142, s[48:49] offset:-2048
	s_waitcnt vmcnt(4)
	v_mfma_f32_32x32x16_bf16 v[52:67], v[246:249], v[238:241], v[52:67]
	global_load_dwordx4 v[246:249], v142, s[46:47] offset:-3072
	s_waitcnt vmcnt(3)
	v_mfma_f32_32x32x16_bf16 v[36:51], v[250:253], v[238:241], v[36:51]
	global_load_dwordx4 v[250:253], v142, s[46:47] offset:-1024
	s_waitcnt vmcnt(3)
	v_mfma_f32_32x32x16_bf16 v[20:35], v[138:141], v[238:241], v[20:35]
	global_load_dwordx4 v[138:141], v142, s[46:47] offset:1024
	s_waitcnt vmcnt(3)
	v_mfma_f32_32x32x16_bf16 v[4:19], v[242:245], v[238:241], v[4:19]
	global_load_dwordx4 v[238:241], v[136:137], off
	v_lshl_add_u64 v[136:137], v[136:137], 0, s[50:51]
	global_load_dwordx4 v[242:245], v142, s[46:47] offset:3072
	s_waitcnt vmcnt(4)
	v_mfma_f32_32x32x16_bf16 v[68:83], v[246:249], v[132:135], v[68:83]
	global_load_dwordx4 v[246:249], v142, s[48:49] offset:-3072
	s_waitcnt vmcnt(4)
	v_mfma_f32_32x32x16_bf16 v[52:67], v[250:253], v[132:135], v[52:67]
	global_load_dwordx4 v[250:253], v142, s[46:47] offset:-4096
	s_waitcnt vmcnt(4)
	v_mfma_f32_32x32x16_bf16 v[36:51], v[138:141], v[132:135], v[36:51]
	global_load_dwordx4 v[138:141], v142, s[46:47] offset:-2048
	s_waitcnt vmcnt(3)
	v_mfma_f32_32x32x16_bf16 v[20:35], v[242:245], v[132:135], v[20:35]
	global_load_dwordx4 v[242:245], v142, s[46:47]
	s_waitcnt vmcnt(3)
	v_mfma_f32_32x32x16_bf16 v[4:19], v[246:249], v[132:135], v[4:19]
	global_load_dwordx4 v[132:135], v[136:137], off
	v_lshl_add_u64 v[136:137], v[136:137], 0, s[50:51]
	global_load_dwordx4 v[246:249], v142, s[46:47] offset:2048
	s_waitcnt vmcnt(4)
	v_mfma_f32_32x32x16_bf16 v[68:83], v[250:253], v[234:237], v[68:83]
	global_load_dwordx4 v[250:253], v142, s[48:49] offset:-4096
	s_waitcnt vmcnt(4)
	v_mfma_f32_32x32x16_bf16 v[52:67], v[138:141], v[234:237], v[52:67]
	global_load_dwordx4 v[138:141], v142, s[46:47] offset:-3072
	s_waitcnt vmcnt(4)
	v_mfma_f32_32x32x16_bf16 v[36:51], v[242:245], v[234:237], v[36:51]
	global_load_dwordx4 v[242:245], v142, s[46:47] offset:-1024
	s_waitcnt vmcnt(3)
	v_mfma_f32_32x32x16_bf16 v[20:35], v[246:249], v[234:237], v[20:35]
	global_load_dwordx4 v[246:249], v142, s[46:47] offset:1024
	s_waitcnt vmcnt(3)
	v_mfma_f32_32x32x16_bf16 v[4:19], v[250:253], v[234:237], v[4:19]
	global_load_dwordx4 v[234:237], v[136:137], off
	v_lshl_add_u64 v[136:137], v[136:137], 0, s[50:51]
	global_load_dwordx4 v[250:253], v142, s[46:47] offset:3072
	s_waitcnt vmcnt(4)
	v_mfma_f32_32x32x16_bf16 v[52:67], v[138:141], v[238:241], v[52:67]
	global_load_dwordx4 v[138:141], v142, s[46:47] offset:-4096
	s_waitcnt vmcnt(4)
	v_mfma_f32_32x32x16_bf16 v[36:51], v[242:245], v[238:241], v[36:51]
	global_load_dwordx4 v[242:245], v142, s[46:47] offset:-2048
	s_waitcnt vmcnt(4)
	v_mfma_f32_32x32x16_bf16 v[20:35], v[246:249], v[238:241], v[20:35]
	global_load_dwordx4 v[246:249], v142, s[46:47]
	s_waitcnt vmcnt(3)
	v_mfma_f32_32x32x16_bf16 v[4:19], v[250:253], v[238:241], v[4:19]
	global_load_dwordx4 v[238:241], v[136:137], off
	v_lshl_add_u64 v[136:137], v[136:137], 0, s[50:51]
	global_load_dwordx4 v[250:253], v142, s[46:47] offset:2048
	s_waitcnt vmcnt(4)
	v_mfma_f32_32x32x16_bf16 v[52:67], v[138:141], v[132:135], v[52:67]
	global_load_dwordx4 v[138:141], v142, s[46:47] offset:-3072
	s_waitcnt vmcnt(4)
	v_mfma_f32_32x32x16_bf16 v[36:51], v[242:245], v[132:135], v[36:51]
	global_load_dwordx4 v[242:245], v142, s[46:47] offset:-1024
	s_waitcnt vmcnt(4)
	v_mfma_f32_32x32x16_bf16 v[20:35], v[246:249], v[132:135], v[20:35]
	global_load_dwordx4 v[246:249], v142, s[46:47] offset:1024
	s_waitcnt vmcnt(3)
	v_mfma_f32_32x32x16_bf16 v[4:19], v[250:253], v[132:135], v[4:19]
	global_load_dwordx4 v[132:135], v[136:137], off
	v_lshl_add_u64 v[136:137], v[136:137], 0, s[50:51]
	global_load_dwordx4 v[250:253], v142, s[46:47] offset:-4096
	s_waitcnt vmcnt(4)
	v_mfma_f32_32x32x16_bf16 v[36:51], v[138:141], v[234:237], v[36:51]
	global_load_dwordx4 v[138:141], v142, s[46:47] offset:-2048
	s_waitcnt vmcnt(4)
	v_mfma_f32_32x32x16_bf16 v[20:35], v[242:245], v[234:237], v[20:35]
	global_load_dwordx4 v[242:245], v142, s[46:47]
	s_waitcnt vmcnt(4)
	v_mfma_f32_32x32x16_bf16 v[4:19], v[246:249], v[234:237], v[4:19]
	global_load_dwordx4 v[234:237], v[136:137], off
	v_lshl_add_u64 v[136:137], v[136:137], 0, s[50:51]
	global_load_dwordx4 v[246:249], v142, s[46:47] offset:-3072
	s_waitcnt vmcnt(4)
	v_mfma_f32_32x32x16_bf16 v[36:51], v[250:253], v[238:241], v[36:51]
	global_load_dwordx4 v[250:253], v142, s[46:47] offset:-1024
	s_waitcnt vmcnt(4)
	v_mfma_f32_32x32x16_bf16 v[20:35], v[138:141], v[238:241], v[20:35]
	global_load_dwordx4 v[138:141], v142, s[46:47] offset:-4096
	s_waitcnt vmcnt(4)
	v_mfma_f32_32x32x16_bf16 v[4:19], v[242:245], v[238:241], v[4:19]
	global_load_dwordx4 v[238:241], v[136:137], off
	v_lshl_add_u64 v[136:137], v[136:137], 0, s[50:51]
	global_load_dwordx4 v[242:245], v142, s[46:47] offset:-2048
	s_waitcnt vmcnt(4)
	v_mfma_f32_32x32x16_bf16 v[20:35], v[246:249], v[132:135], v[20:35]
	global_load_dwordx4 v[246:249], v142, s[46:47] offset:-3072
	s_waitcnt vmcnt(4)
	v_mfma_f32_32x32x16_bf16 v[4:19], v[250:253], v[132:135], v[4:19]
	global_load_dwordx4 v[132:135], v[136:137], off
	v_lshl_add_u64 v[136:137], v[136:137], 0, s[50:51]
	global_load_dwordx4 v[250:253], v142, s[46:47] offset:-4096
	s_waitcnt vmcnt(5)
	v_mfma_f32_32x32x16_bf16 v[20:35], v[138:141], v[234:237], v[20:35]
	s_waitcnt vmcnt(3)
	v_mfma_f32_32x32x16_bf16 v[4:19], v[242:245], v[234:237], v[4:19]
	s_waitcnt vmcnt(2)
	v_mfma_f32_32x32x16_bf16 v[4:19], v[246:249], v[238:241], v[4:19]
	s_waitcnt vmcnt(0)
	v_mfma_f32_32x32x16_bf16 v[4:19], v[250:253], v[132:135], v[4:19]
	s_waitcnt vmcnt(0) lgkmcnt(0)
	s_mov_b32 s3, 16
	s_mov_b32 s42, 0xffffc000
	s_mov_b32 s43, -1
	s_branch .LBB0_814

.LBB0_816:
	s_waitcnt vmcnt(0) lgkmcnt(0)
	v_readfirstlane_b32 s40, v198
	v_readfirstlane_b32 s41, v199
	s_nop 0
	v_subrev_u32_e32 v12, s40, v198
	s_add_u32 s40, s40, 0x1000
	s_addc_u32 s41, s41, 0
	s_add_u32 s42, s40, 0x2000
	s_addc_u32 s43, s41, 0
	s_add_u32 s46, s42, 0x2000
	s_addc_u32 s47, s43, 0
	s_add_u32 s48, s46, 0x2000
	s_addc_u32 s49, s47, 0
	s_mov_b32 s50, 0x2800
	s_mov_b32 s51, 0
	s_nop 4
	global_load_dwordx4 v[4:7], v[200:201], off
	v_lshl_add_u64 v[200:201], v[200:201], 0, s[50:51]
	global_load_dwordx4 v[230:233], v[200:201], off
	v_lshl_add_u64 v[200:201], v[200:201], 0, s[50:51]
	global_load_dwordx4 v[234:237], v[200:201], off
	v_lshl_add_u64 v[200:201], v[200:201], 0, s[50:51]
	global_load_dwordx4 v[238:241], v[200:201], off
	v_lshl_add_u64 v[200:201], v[200:201], 0, s[50:51]
	global_load_dwordx4 v[8:11], v12, s[46:47] offset:-3072
	global_load_dwordx4 v[242:245], v12, s[46:47] offset:-1024
	global_load_dwordx4 v[246:249], v12, s[46:47] offset:1024
	global_load_dwordx4 v[250:253], v12, s[46:47] offset:3072
	s_waitcnt vmcnt(3)
	v_mfma_f32_32x32x16_bf16 v[130:145], v[8:11], v[4:7], v[130:145]
	global_load_dwordx4 v[8:11], v12, s[48:49] offset:-3072
	s_waitcnt vmcnt(3)
	v_mfma_f32_32x32x16_bf16 v[114:129], v[242:245], v[4:7], v[114:129]
	global_load_dwordx4 v[242:245], v12, s[48:49] offset:-1024
	s_waitcnt vmcnt(3)
	v_mfma_f32_32x32x16_bf16 v[98:113], v[246:249], v[4:7], v[98:113]
	global_load_dwordx4 v[246:249], v12, s[48:49] offset:1024
	s_waitcnt vmcnt(3)
	v_mfma_f32_32x32x16_bf16 v[82:97], v[250:253], v[4:7], v[82:97]
	global_load_dwordx4 v[250:253], v12, s[48:49] offset:3072
	s_waitcnt vmcnt(3)
	v_mfma_f32_32x32x16_bf16 v[66:81], v[8:11], v[4:7], v[66:81]
	global_load_dwordx4 v[8:11], v12, s[46:47] offset:-4096
	s_waitcnt vmcnt(3)
	v_mfma_f32_32x32x16_bf16 v[50:65], v[242:245], v[4:7], v[50:65]
	global_load_dwordx4 v[242:245], v12, s[46:47] offset:-2048
	s_waitcnt vmcnt(3)
	v_mfma_f32_32x32x16_bf16 v[34:49], v[246:249], v[4:7], v[34:49]
	global_load_dwordx4 v[246:249], v12, s[46:47]
	s_waitcnt vmcnt(3)
	v_mfma_f32_32x32x16_bf16 v[18:33], v[250:253], v[4:7], v[18:33]
	global_load_dwordx4 v[4:7], v[200:201], off
	v_lshl_add_u64 v[200:201], v[200:201], 0, s[50:51]
	global_load_dwordx4 v[250:253], v12, s[46:47] offset:2048
	s_waitcnt vmcnt(4)
	v_mfma_f32_32x32x16_bf16 v[130:145], v[8:11], v[230:233], v[130:145]
	global_load_dwordx4 v[8:11], v12, s[48:49] offset:-4096
	s_waitcnt vmcnt(4)
	v_mfma_f32_32x32x16_bf16 v[114:129], v[242:245], v[230:233], v[114:129]
	global_load_dwordx4 v[242:245], v12, s[48:49] offset:-2048
	s_waitcnt vmcnt(4)
	v_mfma_f32_32x32x16_bf16 v[98:113], v[246:249], v[230:233], v[98:113]
	global_load_dwordx4 v[246:249], v12, s[48:49]
	s_waitcnt vmcnt(3)
	v_mfma_f32_32x32x16_bf16 v[82:97], v[250:253], v[230:233], v[82:97]
	global_load_dwordx4 v[250:253], v12, s[48:49] offset:2048
	s_waitcnt vmcnt(3)
	v_mfma_f32_32x32x16_bf16 v[66:81], v[8:11], v[230:233], v[66:81]
	global_load_dwordx4 v[8:11], v12, s[42:43] offset:3072
	s_waitcnt vmcnt(3)
	v_mfma_f32_32x32x16_bf16 v[50:65], v[242:245], v[230:233], v[50:65]
	global_load_dwordx4 v[242:245], v12, s[46:47] offset:-3072
	s_waitcnt vmcnt(3)
	v_mfma_f32_32x32x16_bf16 v[34:49], v[246:249], v[230:233], v[34:49]
	global_load_dwordx4 v[246:249], v12, s[46:47] offset:-1024
	s_waitcnt vmcnt(3)
	v_mfma_f32_32x32x16_bf16 v[18:33], v[250:253], v[230:233], v[18:33]
	global_load_dwordx4 v[230:233], v[200:201], off
	v_lshl_add_u64 v[200:201], v[200:201], 0, s[50:51]
	global_load_dwordx4 v[250:253], v12, s[46:47] offset:1024
	s_waitcnt vmcnt(4)
	v_mfma_f32_32x32x16_bf16 v[130:145], v[8:11], v[234:237], v[130:145]
	global_load_dwordx4 v[8:11], v12, s[46:47] offset:3072
	s_waitcnt vmcnt(4)
	v_mfma_f32_32x32x16_bf16 v[114:129], v[242:245], v[234:237], v[114:129]
	global_load_dwordx4 v[242:245], v12, s[48:49] offset:-3072
	s_waitcnt vmcnt(4)
	v_mfma_f32_32x32x16_bf16 v[98:113], v[246:249], v[234:237], v[98:113]
	global_load_dwordx4 v[246:249], v12, s[48:49] offset:-1024
	s_waitcnt vmcnt(3)
	v_mfma_f32_32x32x16_bf16 v[82:97], v[250:253], v[234:237], v[82:97]
	global_load_dwordx4 v[250:253], v12, s[48:49] offset:1024
	s_waitcnt vmcnt(3)
	v_mfma_f32_32x32x16_bf16 v[66:81], v[8:11], v[234:237], v[66:81]
	global_load_dwordx4 v[8:11], v12, s[42:43] offset:2048
	s_waitcnt vmcnt(3)
	v_mfma_f32_32x32x16_bf16 v[50:65], v[242:245], v[234:237], v[50:65]
	global_load_dwordx4 v[242:245], v12, s[46:47] offset:-4096
	s_waitcnt vmcnt(3)
	v_mfma_f32_32x32x16_bf16 v[34:49], v[246:249], v[234:237], v[34:49]
	global_load_dwordx4 v[246:249], v12, s[46:47] offset:-2048
	s_waitcnt vmcnt(3)
	v_mfma_f32_32x32x16_bf16 v[18:33], v[250:253], v[234:237], v[18:33]
	global_load_dwordx4 v[234:237], v[200:201], off
	v_lshl_add_u64 v[200:201], v[200:201], 0, s[50:51]
	global_load_dwordx4 v[250:253], v12, s[46:47]
	s_waitcnt vmcnt(4)
	v_mfma_f32_32x32x16_bf16 v[130:145], v[8:11], v[238:241], v[130:145]
	global_load_dwordx4 v[8:11], v12, s[46:47] offset:2048
	s_waitcnt vmcnt(4)
	v_mfma_f32_32x32x16_bf16 v[114:129], v[242:245], v[238:241], v[114:129]
	global_load_dwordx4 v[242:245], v12, s[48:49] offset:-4096
	s_waitcnt vmcnt(4)
	v_mfma_f32_32x32x16_bf16 v[98:113], v[246:249], v[238:241], v[98:113]
	global_load_dwordx4 v[246:249], v12, s[48:49] offset:-2048
	s_waitcnt vmcnt(3)
	v_mfma_f32_32x32x16_bf16 v[82:97], v[250:253], v[238:241], v[82:97]
	global_load_dwordx4 v[250:253], v12, s[48:49]
	s_waitcnt vmcnt(3)
	v_mfma_f32_32x32x16_bf16 v[66:81], v[8:11], v[238:241], v[66:81]
	global_load_dwordx4 v[8:11], v12, s[42:43] offset:1024
	s_waitcnt vmcnt(3)
	v_mfma_f32_32x32x16_bf16 v[50:65], v[242:245], v[238:241], v[50:65]
	global_load_dwordx4 v[242:245], v12, s[42:43] offset:3072
	s_waitcnt vmcnt(3)
	v_mfma_f32_32x32x16_bf16 v[34:49], v[246:249], v[238:241], v[34:49]
	global_load_dwordx4 v[246:249], v12, s[46:47] offset:-3072
	s_waitcnt vmcnt(3)
	v_mfma_f32_32x32x16_bf16 v[18:33], v[250:253], v[238:241], v[18:33]
	global_load_dwordx4 v[238:241], v[200:201], off
	v_lshl_add_u64 v[200:201], v[200:201], 0, s[50:51]
	global_load_dwordx4 v[250:253], v12, s[46:47] offset:-1024
	s_waitcnt vmcnt(4)
	v_mfma_f32_32x32x16_bf16 v[130:145], v[8:11], v[4:7], v[130:145]
	global_load_dwordx4 v[8:11], v12, s[46:47] offset:1024
	s_waitcnt vmcnt(4)
	v_mfma_f32_32x32x16_bf16 v[114:129], v[242:245], v[4:7], v[114:129]
	global_load_dwordx4 v[242:245], v12, s[46:47] offset:3072
	s_waitcnt vmcnt(4)
	v_mfma_f32_32x32x16_bf16 v[98:113], v[246:249], v[4:7], v[98:113]
	global_load_dwordx4 v[246:249], v12, s[48:49] offset:-3072
	s_waitcnt vmcnt(3)
	v_mfma_f32_32x32x16_bf16 v[82:97], v[250:253], v[4:7], v[82:97]
	global_load_dwordx4 v[250:253], v12, s[48:49] offset:-1024
	s_waitcnt vmcnt(3)
	v_mfma_f32_32x32x16_bf16 v[66:81], v[8:11], v[4:7], v[66:81]
	global_load_dwordx4 v[8:11], v12, s[42:43]
	s_waitcnt vmcnt(3)
	v_mfma_f32_32x32x16_bf16 v[50:65], v[242:245], v[4:7], v[50:65]
	global_load_dwordx4 v[242:245], v12, s[42:43] offset:2048
	s_waitcnt vmcnt(3)
	v_mfma_f32_32x32x16_bf16 v[34:49], v[246:249], v[4:7], v[34:49]
	global_load_dwordx4 v[246:249], v12, s[46:47] offset:-4096
	s_waitcnt vmcnt(3)
	v_mfma_f32_32x32x16_bf16 v[18:33], v[250:253], v[4:7], v[18:33]
	global_load_dwordx4 v[4:7], v[200:201], off
	v_lshl_add_u64 v[200:201], v[200:201], 0, s[50:51]
	global_load_dwordx4 v[250:253], v12, s[46:47] offset:-2048
	s_waitcnt vmcnt(4)
	v_mfma_f32_32x32x16_bf16 v[130:145], v[8:11], v[230:233], v[130:145]
	global_load_dwordx4 v[8:11], v12, s[46:47]
	s_waitcnt vmcnt(4)
	v_mfma_f32_32x32x16_bf16 v[114:129], v[242:245], v[230:233], v[114:129]
	global_load_dwordx4 v[242:245], v12, s[46:47] offset:2048
	s_waitcnt vmcnt(4)
	v_mfma_f32_32x32x16_bf16 v[98:113], v[246:249], v[230:233], v[98:113]
	global_load_dwordx4 v[246:249], v12, s[48:49] offset:-4096
	s_waitcnt vmcnt(3)
	v_mfma_f32_32x32x16_bf16 v[82:97], v[250:253], v[230:233], v[82:97]
	global_load_dwordx4 v[250:253], v12, s[48:49] offset:-2048
	s_waitcnt vmcnt(3)
	v_mfma_f32_32x32x16_bf16 v[66:81], v[8:11], v[230:233], v[66:81]
	global_load_dwordx4 v[8:11], v12, s[42:43] offset:-1024
	s_waitcnt vmcnt(3)
	v_mfma_f32_32x32x16_bf16 v[50:65], v[242:245], v[230:233], v[50:65]
	global_load_dwordx4 v[242:245], v12, s[42:43] offset:1024
	s_waitcnt vmcnt(3)
	v_mfma_f32_32x32x16_bf16 v[34:49], v[246:249], v[230:233], v[34:49]
	global_load_dwordx4 v[246:249], v12, s[42:43] offset:3072
	s_waitcnt vmcnt(3)
	v_mfma_f32_32x32x16_bf16 v[18:33], v[250:253], v[230:233], v[18:33]
	global_load_dwordx4 v[230:233], v[200:201], off
	v_lshl_add_u64 v[200:201], v[200:201], 0, s[50:51]
	global_load_dwordx4 v[250:253], v12, s[46:47] offset:-3072
	s_waitcnt vmcnt(4)
	v_mfma_f32_32x32x16_bf16 v[130:145], v[8:11], v[234:237], v[130:145]
	global_load_dwordx4 v[8:11], v12, s[46:47] offset:-1024
	s_waitcnt vmcnt(4)
	v_mfma_f32_32x32x16_bf16 v[114:129], v[242:245], v[234:237], v[114:129]
	global_load_dwordx4 v[242:245], v12, s[46:47] offset:1024
	s_waitcnt vmcnt(4)
	v_mfma_f32_32x32x16_bf16 v[98:113], v[246:249], v[234:237], v[98:113]
	global_load_dwordx4 v[246:249], v12, s[46:47] offset:3072
	s_waitcnt vmcnt(3)
	v_mfma_f32_32x32x16_bf16 v[82:97], v[250:253], v[234:237], v[82:97]
	global_load_dwordx4 v[250:253], v12, s[48:49] offset:-3072
	s_waitcnt vmcnt(3)
	v_mfma_f32_32x32x16_bf16 v[66:81], v[8:11], v[234:237], v[66:81]
	global_load_dwordx4 v[8:11], v12, s[42:43] offset:-2048
	s_waitcnt vmcnt(3)
	v_mfma_f32_32x32x16_bf16 v[50:65], v[242:245], v[234:237], v[50:65]
	global_load_dwordx4 v[242:245], v12, s[42:43]
	s_waitcnt vmcnt(3)
	v_mfma_f32_32x32x16_bf16 v[34:49], v[246:249], v[234:237], v[34:49]
	global_load_dwordx4 v[246:249], v12, s[42:43] offset:2048
	s_waitcnt vmcnt(3)
	v_mfma_f32_32x32x16_bf16 v[18:33], v[250:253], v[234:237], v[18:33]
	global_load_dwordx4 v[234:237], v[200:201], off
	v_lshl_add_u64 v[200:201], v[200:201], 0, s[50:51]
	global_load_dwordx4 v[250:253], v12, s[46:47] offset:-4096
	s_waitcnt vmcnt(4)
	v_mfma_f32_32x32x16_bf16 v[130:145], v[8:11], v[238:241], v[130:145]
	global_load_dwordx4 v[8:11], v12, s[46:47] offset:-2048
	s_waitcnt vmcnt(4)
	v_mfma_f32_32x32x16_bf16 v[114:129], v[242:245], v[238:241], v[114:129]
	global_load_dwordx4 v[242:245], v12, s[46:47]
	s_waitcnt vmcnt(4)
	v_mfma_f32_32x32x16_bf16 v[98:113], v[246:249], v[238:241], v[98:113]
	global_load_dwordx4 v[246:249], v12, s[46:47] offset:2048
	s_waitcnt vmcnt(3)
	v_mfma_f32_32x32x16_bf16 v[82:97], v[250:253], v[238:241], v[82:97]
	global_load_dwordx4 v[250:253], v12, s[48:49] offset:-4096
	s_waitcnt vmcnt(3)
	v_mfma_f32_32x32x16_bf16 v[66:81], v[8:11], v[238:241], v[66:81]
	global_load_dwordx4 v[8:11], v12, s[42:43] offset:-3072
	s_waitcnt vmcnt(3)
	v_mfma_f32_32x32x16_bf16 v[50:65], v[242:245], v[238:241], v[50:65]
	global_load_dwordx4 v[242:245], v12, s[42:43] offset:-1024
	s_waitcnt vmcnt(3)
	v_mfma_f32_32x32x16_bf16 v[34:49], v[246:249], v[238:241], v[34:49]
	global_load_dwordx4 v[246:249], v12, s[42:43] offset:1024
	s_waitcnt vmcnt(3)
	v_mfma_f32_32x32x16_bf16 v[18:33], v[250:253], v[238:241], v[18:33]
	global_load_dwordx4 v[238:241], v[200:201], off
	v_lshl_add_u64 v[200:201], v[200:201], 0, s[50:51]
	global_load_dwordx4 v[250:253], v12, s[42:43] offset:3072
	s_waitcnt vmcnt(4)
	v_mfma_f32_32x32x16_bf16 v[130:145], v[8:11], v[4:7], v[130:145]
	global_load_dwordx4 v[8:11], v12, s[46:47] offset:-3072
	s_waitcnt vmcnt(4)
	v_mfma_f32_32x32x16_bf16 v[114:129], v[242:245], v[4:7], v[114:129]
	global_load_dwordx4 v[242:245], v12, s[46:47] offset:-1024
	s_waitcnt vmcnt(4)
	v_mfma_f32_32x32x16_bf16 v[98:113], v[246:249], v[4:7], v[98:113]
	global_load_dwordx4 v[246:249], v12, s[46:47] offset:1024
	s_waitcnt vmcnt(3)
	v_mfma_f32_32x32x16_bf16 v[82:97], v[250:253], v[4:7], v[82:97]
	global_load_dwordx4 v[250:253], v12, s[46:47] offset:3072
	s_waitcnt vmcnt(3)
	v_mfma_f32_32x32x16_bf16 v[66:81], v[8:11], v[4:7], v[66:81]
	global_load_dwordx4 v[8:11], v12, s[42:43] offset:-4096
	s_waitcnt vmcnt(3)
	v_mfma_f32_32x32x16_bf16 v[50:65], v[242:245], v[4:7], v[50:65]
	global_load_dwordx4 v[242:245], v12, s[42:43] offset:-2048
	s_waitcnt vmcnt(3)
	v_mfma_f32_32x32x16_bf16 v[34:49], v[246:249], v[4:7], v[34:49]
	global_load_dwordx4 v[246:249], v12, s[42:43]
	s_waitcnt vmcnt(3)
	v_mfma_f32_32x32x16_bf16 v[18:33], v[250:253], v[4:7], v[18:33]
	global_load_dwordx4 v[4:7], v[200:201], off
	v_lshl_add_u64 v[200:201], v[200:201], 0, s[50:51]
	global_load_dwordx4 v[250:253], v12, s[42:43] offset:2048
	s_waitcnt vmcnt(4)
	v_mfma_f32_32x32x16_bf16 v[130:145], v[8:11], v[230:233], v[130:145]
	global_load_dwordx4 v[8:11], v12, s[46:47] offset:-4096
	s_waitcnt vmcnt(4)
	v_mfma_f32_32x32x16_bf16 v[114:129], v[242:245], v[230:233], v[114:129]
	global_load_dwordx4 v[242:245], v12, s[46:47] offset:-2048
	s_waitcnt vmcnt(4)
	v_mfma_f32_32x32x16_bf16 v[98:113], v[246:249], v[230:233], v[98:113]
	global_load_dwordx4 v[246:249], v12, s[46:47]
	s_waitcnt vmcnt(3)
	v_mfma_f32_32x32x16_bf16 v[82:97], v[250:253], v[230:233], v[82:97]
	global_load_dwordx4 v[250:253], v12, s[46:47] offset:2048
	s_waitcnt vmcnt(3)
	v_mfma_f32_32x32x16_bf16 v[66:81], v[8:11], v[230:233], v[66:81]
	global_load_dwordx4 v[8:11], v12, s[40:41] offset:3072
	s_waitcnt vmcnt(3)
	v_mfma_f32_32x32x16_bf16 v[50:65], v[242:245], v[230:233], v[50:65]
	global_load_dwordx4 v[242:245], v12, s[42:43] offset:-3072
	s_waitcnt vmcnt(3)
	v_mfma_f32_32x32x16_bf16 v[34:49], v[246:249], v[230:233], v[34:49]
	global_load_dwordx4 v[246:249], v12, s[42:43] offset:-1024
	s_waitcnt vmcnt(3)
	v_mfma_f32_32x32x16_bf16 v[18:33], v[250:253], v[230:233], v[18:33]
	global_load_dwordx4 v[230:233], v[200:201], off
	v_lshl_add_u64 v[200:201], v[200:201], 0, s[50:51]
	global_load_dwordx4 v[250:253], v12, s[42:43] offset:1024
	s_waitcnt vmcnt(4)
	v_mfma_f32_32x32x16_bf16 v[130:145], v[8:11], v[234:237], v[130:145]
	global_load_dwordx4 v[8:11], v12, s[42:43] offset:3072
	s_waitcnt vmcnt(4)
	v_mfma_f32_32x32x16_bf16 v[114:129], v[242:245], v[234:237], v[114:129]
	global_load_dwordx4 v[242:245], v12, s[46:47] offset:-3072
	s_waitcnt vmcnt(4)
	v_mfma_f32_32x32x16_bf16 v[98:113], v[246:249], v[234:237], v[98:113]
	global_load_dwordx4 v[246:249], v12, s[46:47] offset:-1024
	s_waitcnt vmcnt(3)
	v_mfma_f32_32x32x16_bf16 v[82:97], v[250:253], v[234:237], v[82:97]
	global_load_dwordx4 v[250:253], v12, s[46:47] offset:1024
	s_waitcnt vmcnt(3)
	v_mfma_f32_32x32x16_bf16 v[66:81], v[8:11], v[234:237], v[66:81]
	global_load_dwordx4 v[8:11], v12, s[40:41] offset:2048
	s_waitcnt vmcnt(3)
	v_mfma_f32_32x32x16_bf16 v[50:65], v[242:245], v[234:237], v[50:65]
	global_load_dwordx4 v[242:245], v12, s[42:43] offset:-4096
	s_waitcnt vmcnt(3)
	v_mfma_f32_32x32x16_bf16 v[34:49], v[246:249], v[234:237], v[34:49]
	global_load_dwordx4 v[246:249], v12, s[42:43] offset:-2048
	s_waitcnt vmcnt(3)
	v_mfma_f32_32x32x16_bf16 v[18:33], v[250:253], v[234:237], v[18:33]
	global_load_dwordx4 v[234:237], v[200:201], off
	v_lshl_add_u64 v[200:201], v[200:201], 0, s[50:51]
	global_load_dwordx4 v[250:253], v12, s[42:43]
	s_waitcnt vmcnt(4)
	v_mfma_f32_32x32x16_bf16 v[130:145], v[8:11], v[238:241], v[130:145]
	global_load_dwordx4 v[8:11], v12, s[42:43] offset:2048
	s_waitcnt vmcnt(4)
	v_mfma_f32_32x32x16_bf16 v[114:129], v[242:245], v[238:241], v[114:129]
	global_load_dwordx4 v[242:245], v12, s[46:47] offset:-4096
	s_waitcnt vmcnt(4)
	v_mfma_f32_32x32x16_bf16 v[98:113], v[246:249], v[238:241], v[98:113]
	global_load_dwordx4 v[246:249], v12, s[46:47] offset:-2048
	s_waitcnt vmcnt(3)
	v_mfma_f32_32x32x16_bf16 v[82:97], v[250:253], v[238:241], v[82:97]
	global_load_dwordx4 v[250:253], v12, s[46:47]
	s_waitcnt vmcnt(3)
	v_mfma_f32_32x32x16_bf16 v[66:81], v[8:11], v[238:241], v[66:81]
	global_load_dwordx4 v[8:11], v12, s[40:41] offset:1024
	s_waitcnt vmcnt(3)
	v_mfma_f32_32x32x16_bf16 v[50:65], v[242:245], v[238:241], v[50:65]
	global_load_dwordx4 v[242:245], v12, s[40:41] offset:3072
	s_waitcnt vmcnt(3)
	v_mfma_f32_32x32x16_bf16 v[34:49], v[246:249], v[238:241], v[34:49]
	global_load_dwordx4 v[246:249], v12, s[42:43] offset:-3072
	s_waitcnt vmcnt(3)
	v_mfma_f32_32x32x16_bf16 v[18:33], v[250:253], v[238:241], v[18:33]
	global_load_dwordx4 v[238:241], v[200:201], off
	v_lshl_add_u64 v[200:201], v[200:201], 0, s[50:51]
	global_load_dwordx4 v[250:253], v12, s[42:43] offset:-1024
	s_waitcnt vmcnt(4)
	v_mfma_f32_32x32x16_bf16 v[130:145], v[8:11], v[4:7], v[130:145]
	global_load_dwordx4 v[8:11], v12, s[42:43] offset:1024
	s_waitcnt vmcnt(4)
	v_mfma_f32_32x32x16_bf16 v[114:129], v[242:245], v[4:7], v[114:129]
	global_load_dwordx4 v[242:245], v12, s[42:43] offset:3072
	s_waitcnt vmcnt(4)
	v_mfma_f32_32x32x16_bf16 v[98:113], v[246:249], v[4:7], v[98:113]
	global_load_dwordx4 v[246:249], v12, s[46:47] offset:-3072
	s_waitcnt vmcnt(3)
	v_mfma_f32_32x32x16_bf16 v[82:97], v[250:253], v[4:7], v[82:97]
	global_load_dwordx4 v[250:253], v12, s[46:47] offset:-1024
	s_waitcnt vmcnt(3)
	v_mfma_f32_32x32x16_bf16 v[66:81], v[8:11], v[4:7], v[66:81]
	global_load_dwordx4 v[8:11], v12, s[40:41]
	s_waitcnt vmcnt(3)
	v_mfma_f32_32x32x16_bf16 v[50:65], v[242:245], v[4:7], v[50:65]
	global_load_dwordx4 v[242:245], v12, s[40:41] offset:2048
	s_waitcnt vmcnt(3)
	v_mfma_f32_32x32x16_bf16 v[34:49], v[246:249], v[4:7], v[34:49]
	global_load_dwordx4 v[246:249], v12, s[42:43] offset:-4096
	s_waitcnt vmcnt(3)
	v_mfma_f32_32x32x16_bf16 v[18:33], v[250:253], v[4:7], v[18:33]
	global_load_dwordx4 v[4:7], v[200:201], off
	v_lshl_add_u64 v[200:201], v[200:201], 0, s[50:51]
	global_load_dwordx4 v[250:253], v12, s[42:43] offset:-2048
	s_waitcnt vmcnt(4)
	v_mfma_f32_32x32x16_bf16 v[130:145], v[8:11], v[230:233], v[130:145]
	global_load_dwordx4 v[8:11], v12, s[42:43]
	s_waitcnt vmcnt(4)
	v_mfma_f32_32x32x16_bf16 v[114:129], v[242:245], v[230:233], v[114:129]
	global_load_dwordx4 v[242:245], v12, s[42:43] offset:2048
	s_waitcnt vmcnt(4)
	v_mfma_f32_32x32x16_bf16 v[98:113], v[246:249], v[230:233], v[98:113]
	global_load_dwordx4 v[246:249], v12, s[46:47] offset:-4096
	s_waitcnt vmcnt(3)
	v_mfma_f32_32x32x16_bf16 v[82:97], v[250:253], v[230:233], v[82:97]
	global_load_dwordx4 v[250:253], v12, s[46:47] offset:-2048
	s_waitcnt vmcnt(3)
	v_mfma_f32_32x32x16_bf16 v[66:81], v[8:11], v[230:233], v[66:81]
	global_load_dwordx4 v[8:11], v12, s[40:41] offset:-1024
	s_waitcnt vmcnt(3)
	v_mfma_f32_32x32x16_bf16 v[50:65], v[242:245], v[230:233], v[50:65]
	global_load_dwordx4 v[242:245], v12, s[40:41] offset:1024
	s_waitcnt vmcnt(3)
	v_mfma_f32_32x32x16_bf16 v[34:49], v[246:249], v[230:233], v[34:49]
	global_load_dwordx4 v[246:249], v12, s[40:41] offset:3072
	s_waitcnt vmcnt(3)
	v_mfma_f32_32x32x16_bf16 v[18:33], v[250:253], v[230:233], v[18:33]
	global_load_dwordx4 v[230:233], v[200:201], off
	v_lshl_add_u64 v[200:201], v[200:201], 0, s[50:51]
	global_load_dwordx4 v[250:253], v12, s[42:43] offset:-3072
	s_waitcnt vmcnt(4)
	v_mfma_f32_32x32x16_bf16 v[130:145], v[8:11], v[234:237], v[130:145]
	global_load_dwordx4 v[8:11], v12, s[42:43] offset:-1024
	s_waitcnt vmcnt(4)
	v_mfma_f32_32x32x16_bf16 v[114:129], v[242:245], v[234:237], v[114:129]
	global_load_dwordx4 v[242:245], v12, s[42:43] offset:1024
	s_waitcnt vmcnt(4)
	v_mfma_f32_32x32x16_bf16 v[98:113], v[246:249], v[234:237], v[98:113]
	global_load_dwordx4 v[246:249], v12, s[42:43] offset:3072
	s_waitcnt vmcnt(3)
	v_mfma_f32_32x32x16_bf16 v[82:97], v[250:253], v[234:237], v[82:97]
	global_load_dwordx4 v[250:253], v12, s[46:47] offset:-3072
	s_waitcnt vmcnt(3)
	v_mfma_f32_32x32x16_bf16 v[66:81], v[8:11], v[234:237], v[66:81]
	global_load_dwordx4 v[8:11], v12, s[40:41] offset:-2048
	s_waitcnt vmcnt(3)
	v_mfma_f32_32x32x16_bf16 v[50:65], v[242:245], v[234:237], v[50:65]
	global_load_dwordx4 v[242:245], v12, s[40:41]
	s_waitcnt vmcnt(3)
	v_mfma_f32_32x32x16_bf16 v[34:49], v[246:249], v[234:237], v[34:49]
	global_load_dwordx4 v[246:249], v12, s[40:41] offset:2048
	s_waitcnt vmcnt(3)
	v_mfma_f32_32x32x16_bf16 v[18:33], v[250:253], v[234:237], v[18:33]
	global_load_dwordx4 v[234:237], v[200:201], off
	v_lshl_add_u64 v[200:201], v[200:201], 0, s[50:51]
	global_load_dwordx4 v[250:253], v12, s[42:43] offset:-4096
	s_waitcnt vmcnt(4)
	v_mfma_f32_32x32x16_bf16 v[130:145], v[8:11], v[238:241], v[130:145]
	global_load_dwordx4 v[8:11], v12, s[42:43] offset:-2048
	s_waitcnt vmcnt(4)
	v_mfma_f32_32x32x16_bf16 v[114:129], v[242:245], v[238:241], v[114:129]
	global_load_dwordx4 v[242:245], v12, s[42:43]
	s_waitcnt vmcnt(4)
	v_mfma_f32_32x32x16_bf16 v[98:113], v[246:249], v[238:241], v[98:113]
	global_load_dwordx4 v[246:249], v12, s[42:43] offset:2048
	s_waitcnt vmcnt(3)
	v_mfma_f32_32x32x16_bf16 v[82:97], v[250:253], v[238:241], v[82:97]
	global_load_dwordx4 v[250:253], v12, s[46:47] offset:-4096
	s_waitcnt vmcnt(3)
	v_mfma_f32_32x32x16_bf16 v[66:81], v[8:11], v[238:241], v[66:81]
	global_load_dwordx4 v[8:11], v12, s[40:41] offset:-3072
	s_waitcnt vmcnt(3)
	v_mfma_f32_32x32x16_bf16 v[50:65], v[242:245], v[238:241], v[50:65]
	global_load_dwordx4 v[242:245], v12, s[40:41] offset:-1024
	s_waitcnt vmcnt(3)
	v_mfma_f32_32x32x16_bf16 v[34:49], v[246:249], v[238:241], v[34:49]
	global_load_dwordx4 v[246:249], v12, s[40:41] offset:1024
	s_waitcnt vmcnt(3)
	v_mfma_f32_32x32x16_bf16 v[18:33], v[250:253], v[238:241], v[18:33]
	global_load_dwordx4 v[238:241], v[200:201], off
	v_lshl_add_u64 v[200:201], v[200:201], 0, s[50:51]
	global_load_dwordx4 v[250:253], v12, s[40:41] offset:3072
	s_waitcnt vmcnt(4)
	v_mfma_f32_32x32x16_bf16 v[130:145], v[8:11], v[4:7], v[130:145]
	global_load_dwordx4 v[8:11], v12, s[42:43] offset:-3072
	s_waitcnt vmcnt(4)
	v_mfma_f32_32x32x16_bf16 v[114:129], v[242:245], v[4:7], v[114:129]
	global_load_dwordx4 v[242:245], v12, s[42:43] offset:-1024
	s_waitcnt vmcnt(4)
	v_mfma_f32_32x32x16_bf16 v[98:113], v[246:249], v[4:7], v[98:113]
	global_load_dwordx4 v[246:249], v12, s[42:43] offset:1024
	s_waitcnt vmcnt(3)
	v_mfma_f32_32x32x16_bf16 v[82:97], v[250:253], v[4:7], v[82:97]
	global_load_dwordx4 v[250:253], v12, s[42:43] offset:3072
	s_waitcnt vmcnt(3)
	v_mfma_f32_32x32x16_bf16 v[66:81], v[8:11], v[4:7], v[66:81]
	global_load_dwordx4 v[8:11], v12, s[40:41] offset:-4096
	s_waitcnt vmcnt(3)
	v_mfma_f32_32x32x16_bf16 v[50:65], v[242:245], v[4:7], v[50:65]
	global_load_dwordx4 v[242:245], v12, s[40:41] offset:-2048
	s_waitcnt vmcnt(3)
	v_mfma_f32_32x32x16_bf16 v[34:49], v[246:249], v[4:7], v[34:49]
	global_load_dwordx4 v[246:249], v12, s[40:41]
	s_waitcnt vmcnt(3)
	v_mfma_f32_32x32x16_bf16 v[18:33], v[250:253], v[4:7], v[18:33]
	global_load_dwordx4 v[4:7], v[200:201], off
	v_lshl_add_u64 v[200:201], v[200:201], 0, s[50:51]
	global_load_dwordx4 v[250:253], v12, s[40:41] offset:2048
	s_waitcnt vmcnt(4)
	v_mfma_f32_32x32x16_bf16 v[130:145], v[8:11], v[230:233], v[130:145]
	global_load_dwordx4 v[8:11], v12, s[42:43] offset:-4096
	s_waitcnt vmcnt(4)
	v_mfma_f32_32x32x16_bf16 v[114:129], v[242:245], v[230:233], v[114:129]
	global_load_dwordx4 v[242:245], v12, s[42:43] offset:-2048
	s_waitcnt vmcnt(4)
	v_mfma_f32_32x32x16_bf16 v[98:113], v[246:249], v[230:233], v[98:113]
	global_load_dwordx4 v[246:249], v12, s[42:43]
	s_waitcnt vmcnt(3)
	v_mfma_f32_32x32x16_bf16 v[82:97], v[250:253], v[230:233], v[82:97]
	global_load_dwordx4 v[250:253], v12, s[42:43] offset:2048
	s_waitcnt vmcnt(3)
	v_mfma_f32_32x32x16_bf16 v[66:81], v[8:11], v[230:233], v[66:81]
	global_load_dwordx4 v[8:11], v12, s[40:41] offset:-3072
	s_waitcnt vmcnt(3)
	v_mfma_f32_32x32x16_bf16 v[50:65], v[242:245], v[230:233], v[50:65]
	global_load_dwordx4 v[242:245], v12, s[40:41] offset:-1024
	s_waitcnt vmcnt(3)
	v_mfma_f32_32x32x16_bf16 v[34:49], v[246:249], v[230:233], v[34:49]
	global_load_dwordx4 v[246:249], v12, s[40:41] offset:1024
	s_waitcnt vmcnt(3)
	v_mfma_f32_32x32x16_bf16 v[18:33], v[250:253], v[230:233], v[18:33]
	global_load_dwordx4 v[230:233], v[200:201], off
	v_lshl_add_u64 v[200:201], v[200:201], 0, s[50:51]
	global_load_dwordx4 v[250:253], v12, s[40:41] offset:3072
	s_waitcnt vmcnt(4)
	v_mfma_f32_32x32x16_bf16 v[114:129], v[8:11], v[234:237], v[114:129]
	global_load_dwordx4 v[8:11], v12, s[42:43] offset:-3072
	s_waitcnt vmcnt(4)
	v_mfma_f32_32x32x16_bf16 v[98:113], v[242:245], v[234:237], v[98:113]
	global_load_dwordx4 v[242:245], v12, s[42:43] offset:-1024
	s_waitcnt vmcnt(4)
	v_mfma_f32_32x32x16_bf16 v[82:97], v[246:249], v[234:237], v[82:97]
	global_load_dwordx4 v[246:249], v12, s[42:43] offset:1024
	s_waitcnt vmcnt(3)
	v_mfma_f32_32x32x16_bf16 v[66:81], v[250:253], v[234:237], v[66:81]
	global_load_dwordx4 v[250:253], v12, s[40:41] offset:-4096
	s_waitcnt vmcnt(3)
	v_mfma_f32_32x32x16_bf16 v[50:65], v[8:11], v[234:237], v[50:65]
	global_load_dwordx4 v[8:11], v12, s[40:41] offset:-2048
	s_waitcnt vmcnt(3)
	v_mfma_f32_32x32x16_bf16 v[34:49], v[242:245], v[234:237], v[34:49]
	global_load_dwordx4 v[242:245], v12, s[40:41]
	s_waitcnt vmcnt(3)
	v_mfma_f32_32x32x16_bf16 v[18:33], v[246:249], v[234:237], v[18:33]
	global_load_dwordx4 v[234:237], v[200:201], off
	v_lshl_add_u64 v[200:201], v[200:201], 0, s[50:51]
	global_load_dwordx4 v[246:249], v12, s[40:41] offset:2048
	s_waitcnt vmcnt(4)
	v_mfma_f32_32x32x16_bf16 v[114:129], v[250:253], v[238:241], v[114:129]
	global_load_dwordx4 v[250:253], v12, s[42:43] offset:-4096
	s_waitcnt vmcnt(4)
	v_mfma_f32_32x32x16_bf16 v[98:113], v[8:11], v[238:241], v[98:113]
	global_load_dwordx4 v[8:11], v12, s[42:43] offset:-2048
	s_waitcnt vmcnt(4)
	v_mfma_f32_32x32x16_bf16 v[82:97], v[242:245], v[238:241], v[82:97]
	global_load_dwordx4 v[242:245], v12, s[42:43]
	s_waitcnt vmcnt(3)
	v_mfma_f32_32x32x16_bf16 v[66:81], v[246:249], v[238:241], v[66:81]
	global_load_dwordx4 v[246:249], v12, s[40:41] offset:-3072
	s_waitcnt vmcnt(3)
	v_mfma_f32_32x32x16_bf16 v[50:65], v[250:253], v[238:241], v[50:65]
	global_load_dwordx4 v[250:253], v12, s[40:41] offset:-1024
	s_waitcnt vmcnt(3)
	v_mfma_f32_32x32x16_bf16 v[34:49], v[8:11], v[238:241], v[34:49]
	global_load_dwordx4 v[8:11], v12, s[40:41] offset:1024
	s_waitcnt vmcnt(3)
	v_mfma_f32_32x32x16_bf16 v[18:33], v[242:245], v[238:241], v[18:33]
	global_load_dwordx4 v[238:241], v[200:201], off
	v_lshl_add_u64 v[200:201], v[200:201], 0, s[50:51]
	global_load_dwordx4 v[242:245], v12, s[40:41] offset:3072
	s_waitcnt vmcnt(4)
	v_mfma_f32_32x32x16_bf16 v[98:113], v[246:249], v[4:7], v[98:113]
	global_load_dwordx4 v[246:249], v12, s[42:43] offset:-3072
	s_waitcnt vmcnt(4)
	v_mfma_f32_32x32x16_bf16 v[82:97], v[250:253], v[4:7], v[82:97]
	global_load_dwordx4 v[250:253], v12, s[42:43] offset:-1024
	s_waitcnt vmcnt(4)
	v_mfma_f32_32x32x16_bf16 v[66:81], v[8:11], v[4:7], v[66:81]
	global_load_dwordx4 v[8:11], v12, s[40:41] offset:-4096
	s_waitcnt vmcnt(3)
	v_mfma_f32_32x32x16_bf16 v[50:65], v[242:245], v[4:7], v[50:65]
	global_load_dwordx4 v[242:245], v12, s[40:41] offset:-2048
	s_waitcnt vmcnt(3)
	v_mfma_f32_32x32x16_bf16 v[34:49], v[246:249], v[4:7], v[34:49]
	global_load_dwordx4 v[246:249], v12, s[40:41]
	s_waitcnt vmcnt(3)
	v_mfma_f32_32x32x16_bf16 v[18:33], v[250:253], v[4:7], v[18:33]
	global_load_dwordx4 v[4:7], v[200:201], off
	v_lshl_add_u64 v[200:201], v[200:201], 0, s[50:51]
	global_load_dwordx4 v[250:253], v12, s[40:41] offset:2048
	s_waitcnt vmcnt(4)
	v_mfma_f32_32x32x16_bf16 v[98:113], v[8:11], v[230:233], v[98:113]
	global_load_dwordx4 v[8:11], v12, s[42:43] offset:-4096
	s_waitcnt vmcnt(4)
	v_mfma_f32_32x32x16_bf16 v[82:97], v[242:245], v[230:233], v[82:97]
	global_load_dwordx4 v[242:245], v12, s[42:43] offset:-2048
	s_waitcnt vmcnt(4)
	v_mfma_f32_32x32x16_bf16 v[66:81], v[246:249], v[230:233], v[66:81]
	global_load_dwordx4 v[246:249], v12, s[40:41] offset:-3072
	s_waitcnt vmcnt(3)
	v_mfma_f32_32x32x16_bf16 v[50:65], v[250:253], v[230:233], v[50:65]
	global_load_dwordx4 v[250:253], v12, s[40:41] offset:-1024
	s_waitcnt vmcnt(3)
	v_mfma_f32_32x32x16_bf16 v[34:49], v[8:11], v[230:233], v[34:49]
	global_load_dwordx4 v[8:11], v12, s[40:41] offset:1024
	s_waitcnt vmcnt(3)
	v_mfma_f32_32x32x16_bf16 v[18:33], v[242:245], v[230:233], v[18:33]
	global_load_dwordx4 v[230:233], v[200:201], off
	v_lshl_add_u64 v[200:201], v[200:201], 0, s[50:51]
	global_load_dwordx4 v[242:245], v12, s[40:41] offset:3072
	s_waitcnt vmcnt(4)
	v_mfma_f32_32x32x16_bf16 v[82:97], v[246:249], v[234:237], v[82:97]
	global_load_dwordx4 v[246:249], v12, s[42:43] offset:-3072
	s_waitcnt vmcnt(4)
	v_mfma_f32_32x32x16_bf16 v[66:81], v[250:253], v[234:237], v[66:81]
	global_load_dwordx4 v[250:253], v12, s[40:41] offset:-4096
	s_waitcnt vmcnt(4)
	v_mfma_f32_32x32x16_bf16 v[50:65], v[8:11], v[234:237], v[50:65]
	global_load_dwordx4 v[8:11], v12, s[40:41] offset:-2048
	s_waitcnt vmcnt(3)
	v_mfma_f32_32x32x16_bf16 v[34:49], v[242:245], v[234:237], v[34:49]
	global_load_dwordx4 v[242:245], v12, s[40:41]
	s_waitcnt vmcnt(3)
	v_mfma_f32_32x32x16_bf16 v[18:33], v[246:249], v[234:237], v[18:33]
	global_load_dwordx4 v[234:237], v[200:201], off
	v_lshl_add_u64 v[200:201], v[200:201], 0, s[50:51]
	global_load_dwordx4 v[246:249], v12, s[40:41] offset:2048
	s_waitcnt vmcnt(4)
	v_mfma_f32_32x32x16_bf16 v[82:97], v[250:253], v[238:241], v[82:97]
	global_load_dwordx4 v[250:253], v12, s[42:43] offset:-4096
	s_waitcnt vmcnt(4)
	v_mfma_f32_32x32x16_bf16 v[66:81], v[8:11], v[238:241], v[66:81]
	global_load_dwordx4 v[8:11], v12, s[40:41] offset:-3072
	s_waitcnt vmcnt(4)
	v_mfma_f32_32x32x16_bf16 v[50:65], v[242:245], v[238:241], v[50:65]
	global_load_dwordx4 v[242:245], v12, s[40:41] offset:-1024
	s_waitcnt vmcnt(3)
	v_mfma_f32_32x32x16_bf16 v[34:49], v[246:249], v[238:241], v[34:49]
	global_load_dwordx4 v[246:249], v12, s[40:41] offset:1024
	s_waitcnt vmcnt(3)
	v_mfma_f32_32x32x16_bf16 v[18:33], v[250:253], v[238:241], v[18:33]
	global_load_dwordx4 v[238:241], v[200:201], off
	v_lshl_add_u64 v[200:201], v[200:201], 0, s[50:51]
	global_load_dwordx4 v[250:253], v12, s[40:41] offset:3072
	s_waitcnt vmcnt(4)
	v_mfma_f32_32x32x16_bf16 v[66:81], v[8:11], v[4:7], v[66:81]
	global_load_dwordx4 v[8:11], v12, s[40:41] offset:-4096
	s_waitcnt vmcnt(4)
	v_mfma_f32_32x32x16_bf16 v[50:65], v[242:245], v[4:7], v[50:65]
	global_load_dwordx4 v[242:245], v12, s[40:41] offset:-2048
	s_waitcnt vmcnt(4)
	v_mfma_f32_32x32x16_bf16 v[34:49], v[246:249], v[4:7], v[34:49]
	global_load_dwordx4 v[246:249], v12, s[40:41]
	s_waitcnt vmcnt(3)
	v_mfma_f32_32x32x16_bf16 v[18:33], v[250:253], v[4:7], v[18:33]
	global_load_dwordx4 v[4:7], v[200:201], off
	v_lshl_add_u64 v[200:201], v[200:201], 0, s[50:51]
	global_load_dwordx4 v[250:253], v12, s[40:41] offset:2048
	s_waitcnt vmcnt(4)
	v_mfma_f32_32x32x16_bf16 v[66:81], v[8:11], v[230:233], v[66:81]
	global_load_dwordx4 v[8:11], v12, s[40:41] offset:-3072
	s_waitcnt vmcnt(4)
	v_mfma_f32_32x32x16_bf16 v[50:65], v[242:245], v[230:233], v[50:65]
	global_load_dwordx4 v[242:245], v12, s[40:41] offset:-1024
	s_waitcnt vmcnt(4)
	v_mfma_f32_32x32x16_bf16 v[34:49], v[246:249], v[230:233], v[34:49]
	global_load_dwordx4 v[246:249], v12, s[40:41] offset:1024
	s_waitcnt vmcnt(3)
	v_mfma_f32_32x32x16_bf16 v[18:33], v[250:253], v[230:233], v[18:33]
	global_load_dwordx4 v[230:233], v[200:201], off
	v_lshl_add_u64 v[200:201], v[200:201], 0, s[50:51]
	global_load_dwordx4 v[250:253], v12, s[40:41] offset:-4096
	s_waitcnt vmcnt(4)
	v_mfma_f32_32x32x16_bf16 v[50:65], v[8:11], v[234:237], v[50:65]
	global_load_dwordx4 v[8:11], v12, s[40:41] offset:-2048
	s_waitcnt vmcnt(4)
	v_mfma_f32_32x32x16_bf16 v[34:49], v[242:245], v[234:237], v[34:49]
	global_load_dwordx4 v[242:245], v12, s[40:41]
	s_waitcnt vmcnt(4)
	v_mfma_f32_32x32x16_bf16 v[18:33], v[246:249], v[234:237], v[18:33]
	global_load_dwordx4 v[234:237], v[200:201], off
	v_lshl_add_u64 v[200:201], v[200:201], 0, s[50:51]
	global_load_dwordx4 v[246:249], v12, s[40:41] offset:-3072
	s_waitcnt vmcnt(4)
	v_mfma_f32_32x32x16_bf16 v[50:65], v[250:253], v[238:241], v[50:65]
	global_load_dwordx4 v[250:253], v12, s[40:41] offset:-1024
	s_waitcnt vmcnt(4)
	v_mfma_f32_32x32x16_bf16 v[34:49], v[8:11], v[238:241], v[34:49]
	global_load_dwordx4 v[8:11], v12, s[40:41] offset:-4096
	s_waitcnt vmcnt(4)
	v_mfma_f32_32x32x16_bf16 v[18:33], v[242:245], v[238:241], v[18:33]
	global_load_dwordx4 v[238:241], v[200:201], off
	v_lshl_add_u64 v[200:201], v[200:201], 0, s[50:51]
	global_load_dwordx4 v[242:245], v12, s[40:41] offset:-2048
	s_waitcnt vmcnt(4)
	v_mfma_f32_32x32x16_bf16 v[34:49], v[246:249], v[4:7], v[34:49]
	global_load_dwordx4 v[246:249], v12, s[40:41] offset:-3072
	s_waitcnt vmcnt(4)
	v_mfma_f32_32x32x16_bf16 v[18:33], v[250:253], v[4:7], v[18:33]
	global_load_dwordx4 v[250:253], v12, s[40:41] offset:-4096
	s_waitcnt vmcnt(4)
	v_mfma_f32_32x32x16_bf16 v[34:49], v[8:11], v[230:233], v[34:49]
	s_waitcnt vmcnt(2)
	v_mfma_f32_32x32x16_bf16 v[18:33], v[242:245], v[230:233], v[18:33]
	s_waitcnt vmcnt(1)
	v_mfma_f32_32x32x16_bf16 v[18:33], v[246:249], v[234:237], v[18:33]
	s_waitcnt vmcnt(0)
	v_mfma_f32_32x32x16_bf16 v[18:33], v[250:253], v[238:241], v[18:33]
	s_waitcnt vmcnt(0) lgkmcnt(0)
	s_mov_b32 s3, 32
	s_mov_b32 s34, 0xffff8000
	s_mov_b32 s35, -1
	s_branch .LBB0_769
